# M1 parking epilogue: the sixteen gate-chunk loads issued together up front, counted wait per chunk instead of waiting for stores and staging loads
# baseline (speedup 1.0000x reference)
; __device__ __forceinline__ float bf_lo(unsigned u) { return __uint_as_float(u << 16); }
; __device__ __forceinline__ float bf_hi(unsigned u) { return __uint_as_float(u & 0xffff0000u); }
; __device__ __forceinline__ int launder_i(int x) { asm volatile("" : "+v"(x)); return x; }
; __device__ __forceinline__ void gemm_prologue(const GemmSrc& g, char* lds) { gemm_issue(g, 0, 0, lds); }
; __device__ void phaseM1(const Params& p, char* lds) {
;     ...
;                 g = gemm_src(H, DM, (const bf16_t*)(p.ws + OFF_WM) + (size_t)1024 * 1024, DM, m0, n0);
;                 gemm_prologue(g, lds);
;             }
;             if (br == 0) {
; #pragma unroll
;                 for (int mi = 0; mi < 8; mi++)
; #pragma unroll
;                     for (int nh = 0; nh < 2; nh++) {
;                         const u32x4 sg = SG[(size_t)launder_i(pbase + (mi * 2 + nh) * 512)];
;                         const f32x4 a0 = acc[mi][2 * nh], a1 = acc[mi][2 * nh + 1];
;                         PA[(size_t)launder_i(pbase + (mi * 2 + nh) * 512)] = (u32x4){pack2(bf_lo(sg.x) * a0[0], bf_hi(sg.x) * a0[1]), pack2(bf_lo(sg.y) * a0[2], bf_hi(sg.y) * a0[3]),
;                                                                           pack2(bf_lo(sg.z) * a1[0], bf_hi(sg.z) * a1[1]), pack2(bf_lo(sg.w) * a1[2], bf_hi(sg.w) * a1[3])};
;                     }
.LBB0_722:
	v_mov_b32_e32 v184, v146
	v_ashrrev_i32_e32 v185, 31, v146
	v_mov_b32_e32 v188, v147
	v_ashrrev_i32_e32 v189, 31, v147
	v_mov_b32_e32 v192, v148
	v_ashrrev_i32_e32 v193, 31, v148
	v_mov_b32_e32 v196, v149
	v_ashrrev_i32_e32 v197, 31, v149
	v_mov_b32_e32 v200, v150
	v_ashrrev_i32_e32 v201, 31, v150
	v_mov_b32_e32 v204, v151
	v_ashrrev_i32_e32 v205, 31, v151
	v_mov_b32_e32 v208, v152
	v_ashrrev_i32_e32 v209, 31, v152
	v_mov_b32_e32 v212, v153
	v_ashrrev_i32_e32 v213, 31, v153
	v_mov_b32_e32 v216, v154
	v_ashrrev_i32_e32 v217, 31, v154
	v_mov_b32_e32 v224, v155
	v_ashrrev_i32_e32 v225, 31, v155
	v_mov_b32_e32 v228, v156
	v_ashrrev_i32_e32 v229, 31, v156
	v_mov_b32_e32 v232, v157
	v_ashrrev_i32_e32 v233, 31, v157
	v_mov_b32_e32 v236, v160
	v_ashrrev_i32_e32 v237, 31, v160
	v_mov_b32_e32 v240, v161
	v_ashrrev_i32_e32 v241, 31, v161
	v_mov_b32_e32 v244, v162
	v_ashrrev_i32_e32 v245, 31, v162
	v_mov_b32_e32 v248, v163
	v_ashrrev_i32_e32 v249, 31, v163
	v_lshl_add_u64 v[184:185], v[184:185], 4, s[4:5]
	v_lshl_add_u64 v[188:189], v[188:189], 4, s[4:5]
	v_lshl_add_u64 v[192:193], v[192:193], 4, s[4:5]
	v_lshl_add_u64 v[196:197], v[196:197], 4, s[4:5]
	v_lshl_add_u64 v[200:201], v[200:201], 4, s[4:5]
	v_lshl_add_u64 v[204:205], v[204:205], 4, s[4:5]
	v_lshl_add_u64 v[208:209], v[208:209], 4, s[4:5]
	v_lshl_add_u64 v[212:213], v[212:213], 4, s[4:5]
	v_lshl_add_u64 v[216:217], v[216:217], 4, s[4:5]
	v_lshl_add_u64 v[224:225], v[224:225], 4, s[4:5]
	v_lshl_add_u64 v[228:229], v[228:229], 4, s[4:5]
	v_lshl_add_u64 v[232:233], v[232:233], 4, s[4:5]
	v_lshl_add_u64 v[236:237], v[236:237], 4, s[4:5]
	v_lshl_add_u64 v[240:241], v[240:241], 4, s[4:5]
	v_lshl_add_u64 v[244:245], v[244:245], 4, s[4:5]
	v_lshl_add_u64 v[248:249], v[248:249], 4, s[4:5]
	global_load_dwordx4 v[184:187], v[184:185], off
	global_load_dwordx4 v[188:191], v[188:189], off
	global_load_dwordx4 v[192:195], v[192:193], off
	global_load_dwordx4 v[196:199], v[196:197], off
	global_load_dwordx4 v[200:203], v[200:201], off
	global_load_dwordx4 v[204:207], v[204:205], off
	global_load_dwordx4 v[208:211], v[208:209], off
	global_load_dwordx4 v[212:215], v[212:213], off
	global_load_dwordx4 v[216:219], v[216:217], off
	global_load_dwordx4 v[224:227], v[224:225], off
	global_load_dwordx4 v[228:231], v[228:229], off
	global_load_dwordx4 v[232:235], v[232:233], off
	global_load_dwordx4 v[236:239], v[236:237], off
	global_load_dwordx4 v[240:243], v[240:241], off
	global_load_dwordx4 v[244:247], v[244:245], off
	global_load_dwordx4 v[248:251], v[248:249], off
	v_mov_b32_e32 v128, v158
	s_mov_b64 s[56:57], 0x400
	v_ashrrev_i32_e32 v130, 1, v128
	v_bfe_u32 v131, v128, 3, 3
	v_and_or_b32 v134, v130, s63, v131
	v_bfe_u32 v130, v128, 4, 2
	v_and_b32_e32 v131, 7, v128
	v_bitop3_b32 v135, v130, v128, 7 bitop3:0x78
	v_bitop3_b32 v136, v130, v131, 4 bitop3:0x36
	v_add_u32_e32 v130, s74, v134
	v_ashrrev_i32_e32 v131, 31, v130
	v_lshlrev_b64 v[130:131], 11, v[130:131]
	v_lshl_add_u64 v[130:131], s[8:9], 0, v[130:131]
	v_lshlrev_b32_e32 v128, 4, v135
	v_lshl_add_u64 v[132:133], v[130:131], 0, v[128:129]
	v_add_u32_e32 v130, s48, v134
	v_ashrrev_i32_e32 v131, 31, v130
	v_lshlrev_b64 v[130:131], 11, v[130:131]
	v_lshl_add_u64 v[130:131], s[14:15], 0, v[130:131]
	v_lshl_add_u64 v[130:131], v[130:131], 0, v[128:129]
	v_sub_u32_e32 v128, v136, v135
	v_lshlrev_b32_e32 v134, 3, v128
	v_mov_b32_e32 v128, v158
	s_nop 0
	v_lshlrev_b32_e32 v135, 6, v128
	v_lshlrev_b32_e32 v128, 4, v128
	v_and_b32_e32 v128, 0x3f0, v128
	v_and_or_b32 v128, v135, s65, v128
	v_add_u32_e32 v135, 0x8000, v128
	v_readfirstlane_b32 s0, v128
	s_mov_b32 m0, s0
	v_readfirstlane_b32 s0, v135
	v_ashrrev_i32_e32 v135, 31, v134
	v_lshlrev_b64 v[136:137], 1, v[134:135]
	v_or_b32_e32 v135, 0x400, v128
	global_load_lds_dwordx4 v[132:133], off
	s_mov_b32 m0, s0
	v_lshl_add_u64 v[138:139], v[132:133], 0, v[136:137]
	v_readfirstlane_b32 s0, v135
	v_add_u32_e32 v135, 0x8400, v128
	global_load_lds_dwordx4 v[130:131], off
	v_lshl_add_u64 v[140:141], v[138:139], 0, s[16:17]
	s_mov_b32 m0, s0
	v_lshl_add_u64 v[136:137], v[130:131], 0, v[136:137]
	v_readfirstlane_b32 s0, v135
	v_or_b32_e32 v135, 0x800, v128
	global_load_lds_dwordx4 v[140:141], off
	v_lshl_add_u64 v[140:141], v[136:137], 0, s[16:17]
	s_mov_b32 m0, s0
	v_readfirstlane_b32 s0, v135
	v_add_u32_e32 v135, 0x8800, v128
	global_load_lds_dwordx4 v[140:141], off
	v_lshl_add_u64 v[140:141], v[132:133], 0, s[18:19]
	s_mov_b32 m0, s0
	v_readfirstlane_b32 s0, v135
	v_or_b32_e32 v135, 0xc00, v128
	global_load_lds_dwordx4 v[140:141], off
	v_lshl_add_u64 v[140:141], v[130:131], 0, s[18:19]
	s_mov_b32 m0, s0
	v_readfirstlane_b32 s0, v135
	v_add_u32_e32 v128, 0x8c00, v128
	global_load_lds_dwordx4 v[140:141], off
	v_lshl_add_u64 v[138:139], v[138:139], 0, s[20:21]
	s_mov_b32 m0, s0
	v_readfirstlane_b32 s0, v128
	global_load_lds_dwordx4 v[138:139], off
	v_lshl_add_u64 v[136:137], v[136:137], 0, s[20:21]
	s_mov_b32 m0, s0
	v_mov_b32_e32 v140, v146
	global_load_lds_dwordx4 v[136:137], off
	v_mov_b32_e32 v136, v146
	s_nop 0
	v_ashrrev_i32_e32 v137, 31, v136
	v_lshl_add_u64 v[136:137], v[136:137], 4, s[4:5]
	s_waitcnt vmcnt(23)
; __device__ __forceinline__ float bf_lo(unsigned u) { return __uint_as_float(u << 16); }
; __device__ __forceinline__ float bf_hi(unsigned u) { return __uint_as_float(u & 0xffff0000u); }
; __device__ __forceinline__ int launder_i(int x) { asm volatile("" : "+v"(x)); return x; }
; __device__ void phaseM1(const Params& p, char* lds) {
;     ...
;             if (br == 0) {
; #pragma unroll
;                 for (int mi = 0; mi < 8; mi++)
; #pragma unroll
;                     for (int nh = 0; nh < 2; nh++) {
;                         const u32x4 sg = SG[(size_t)launder_i(pbase + (mi * 2 + nh) * 512)];
;                         const f32x4 a0 = acc[mi][2 * nh], a1 = acc[mi][2 * nh + 1];
;                         PA[(size_t)launder_i(pbase + (mi * 2 + nh) * 512)] = (u32x4){pack2(bf_lo(sg.x) * a0[0], bf_hi(sg.x) * a0[1]), pack2(bf_lo(sg.y) * a0[2], bf_hi(sg.y) * a0[3]),
;                                                                           pack2(bf_lo(sg.z) * a1[0], bf_hi(sg.z) * a1[1]), pack2(bf_lo(sg.w) * a1[2], bf_hi(sg.w) * a1[3])};
;                     }
	v_mov_b32_e32 v136, v184
	v_mov_b32_e32 v137, v185
	v_mov_b32_e32 v138, v186
	v_mov_b32_e32 v139, v187
	v_lshlrev_b32_e32 v142, 16, v136
	v_and_b32_e32 v143, 0xffff0000, v136
	v_lshlrev_b32_e32 v136, 16, v137
	v_and_b32_e32 v137, 0xffff0000, v137
	v_lshlrev_b32_e32 v164, 16, v138
	v_and_b32_e32 v165, 0xffff0000, v138
	v_lshlrev_b32_e32 v138, 16, v139
	v_and_b32_e32 v139, 0xffff0000, v139
	v_ashrrev_i32_e32 v141, 31, v140
	v_pk_mul_f32 v[124:125], v[124:125], v[142:143]
	v_pk_mul_f32 v[126:127], v[126:127], v[136:137]
	v_pk_mul_f32 v[136:137], v[120:121], v[164:165]
	v_pk_mul_f32 v[138:139], v[122:123], v[138:139]
	v_lshl_add_u64 v[140:141], v[140:141], 4, s[10:11]
	v_cvt_pk_bf16_f32 v120, v124, v125
	v_cvt_pk_bf16_f32 v121, v126, v127
	v_cvt_pk_bf16_f32 v122, v136, v137
	v_cvt_pk_bf16_f32 v123, v138, v139
	global_store_dwordx4 v[140:141], v[120:123], off
	v_mov_b32_e32 v124, v147
	v_mov_b32_e32 v126, v148
	v_mov_b32_e32 v120, v147
	s_nop 0
	v_ashrrev_i32_e32 v121, 31, v120
	v_lshl_add_u64 v[120:121], v[120:121], 4, s[4:5]
	s_waitcnt vmcnt(23)
	v_mov_b32_e32 v120, v188
	v_mov_b32_e32 v121, v189
	v_mov_b32_e32 v122, v190
	v_mov_b32_e32 v123, v191
	v_lshlrev_b32_e32 v136, 16, v120
	v_and_b32_e32 v137, 0xffff0000, v120
	v_lshlrev_b32_e32 v120, 16, v121
	v_and_b32_e32 v121, 0xffff0000, v121
	v_lshlrev_b32_e32 v138, 16, v122
	v_and_b32_e32 v139, 0xffff0000, v122
	v_lshlrev_b32_e32 v122, 16, v123
	v_and_b32_e32 v123, 0xffff0000, v123
	v_ashrrev_i32_e32 v125, 31, v124
	v_pk_mul_f32 v[116:117], v[116:117], v[136:137]
	v_pk_mul_f32 v[118:119], v[118:119], v[120:121]
	v_pk_mul_f32 v[120:121], v[112:113], v[138:139]
	v_pk_mul_f32 v[122:123], v[114:115], v[122:123]
	v_lshl_add_u64 v[124:125], v[124:125], 4, s[10:11]
	v_cvt_pk_bf16_f32 v112, v116, v117
	v_cvt_pk_bf16_f32 v113, v118, v119
	v_cvt_pk_bf16_f32 v114, v120, v121
	v_cvt_pk_bf16_f32 v115, v122, v123
	global_store_dwordx4 v[124:125], v[112:115], off
	v_mov_b32_e32 v116, v148
	v_ashrrev_i32_e32 v127, 31, v126
	v_lshl_add_u64 v[112:113], v[126:127], 4, s[4:5]
	v_mov_b32_e32 v118, v149
	v_ashrrev_i32_e32 v117, 31, v116
	v_lshl_add_u64 v[116:117], v[116:117], 4, s[10:11]
	s_waitcnt vmcnt(23)
	v_mov_b32_e32 v112, v192
	v_mov_b32_e32 v113, v193
	v_mov_b32_e32 v114, v194
	v_mov_b32_e32 v115, v195
	v_lshlrev_b32_e32 v120, 16, v112
	v_and_b32_e32 v121, 0xffff0000, v112
	v_lshlrev_b32_e32 v112, 16, v113
	v_and_b32_e32 v113, 0xffff0000, v113
	v_lshlrev_b32_e32 v122, 16, v114
	v_and_b32_e32 v123, 0xffff0000, v114
	v_lshlrev_b32_e32 v114, 16, v115
	v_and_b32_e32 v115, 0xffff0000, v115
	v_pk_mul_f32 v[108:109], v[108:109], v[120:121]
	v_pk_mul_f32 v[110:111], v[110:111], v[112:113]
	v_pk_mul_f32 v[112:113], v[104:105], v[122:123]
	v_pk_mul_f32 v[114:115], v[106:107], v[114:115]
	v_cvt_pk_bf16_f32 v104, v108, v109
	v_cvt_pk_bf16_f32 v105, v110, v111
	v_cvt_pk_bf16_f32 v106, v112, v113
	v_cvt_pk_bf16_f32 v107, v114, v115
	global_store_dwordx4 v[116:117], v[104:107], off
	v_mov_b32_e32 v108, v149
	v_ashrrev_i32_e32 v119, 31, v118
	v_lshl_add_u64 v[104:105], v[118:119], 4, s[4:5]
	v_mov_b32_e32 v110, v150
	v_ashrrev_i32_e32 v109, 31, v108
	v_lshl_add_u64 v[108:109], v[108:109], 4, s[10:11]
	s_waitcnt vmcnt(23)
	v_mov_b32_e32 v104, v196
	v_mov_b32_e32 v105, v197
	v_mov_b32_e32 v106, v198
	v_mov_b32_e32 v107, v199
	v_lshlrev_b32_e32 v112, 16, v104
	v_and_b32_e32 v113, 0xffff0000, v104
	v_lshlrev_b32_e32 v104, 16, v105
	v_and_b32_e32 v105, 0xffff0000, v105
	v_lshlrev_b32_e32 v114, 16, v106
	v_and_b32_e32 v115, 0xffff0000, v106
	v_lshlrev_b32_e32 v106, 16, v107
	v_and_b32_e32 v107, 0xffff0000, v107
	v_pk_mul_f32 v[100:101], v[100:101], v[112:113]
	v_pk_mul_f32 v[102:103], v[102:103], v[104:105]
	v_pk_mul_f32 v[104:105], v[96:97], v[114:115]
	v_pk_mul_f32 v[106:107], v[98:99], v[106:107]
	v_cvt_pk_bf16_f32 v96, v100, v101
	v_cvt_pk_bf16_f32 v97, v102, v103
	v_cvt_pk_bf16_f32 v98, v104, v105
	v_cvt_pk_bf16_f32 v99, v106, v107
	global_store_dwordx4 v[108:109], v[96:99], off
	v_mov_b32_e32 v100, v150
	v_ashrrev_i32_e32 v111, 31, v110
	v_lshl_add_u64 v[96:97], v[110:111], 4, s[4:5]
	v_mov_b32_e32 v102, v151
	v_ashrrev_i32_e32 v101, 31, v100
	v_lshl_add_u64 v[100:101], v[100:101], 4, s[10:11]
	s_waitcnt vmcnt(23)
	v_mov_b32_e32 v96, v200
	v_mov_b32_e32 v97, v201
	v_mov_b32_e32 v98, v202
	v_mov_b32_e32 v99, v203
	v_lshlrev_b32_e32 v104, 16, v96
	v_and_b32_e32 v105, 0xffff0000, v96
	v_lshlrev_b32_e32 v96, 16, v97
	v_and_b32_e32 v97, 0xffff0000, v97
	v_lshlrev_b32_e32 v106, 16, v98
	v_and_b32_e32 v107, 0xffff0000, v98
	v_lshlrev_b32_e32 v98, 16, v99
	v_and_b32_e32 v99, 0xffff0000, v99
	v_pk_mul_f32 v[92:93], v[92:93], v[104:105]
	v_pk_mul_f32 v[94:95], v[94:95], v[96:97]
	v_pk_mul_f32 v[96:97], v[88:89], v[106:107]
	v_pk_mul_f32 v[98:99], v[90:91], v[98:99]
	v_cvt_pk_bf16_f32 v88, v92, v93
	v_cvt_pk_bf16_f32 v89, v94, v95
	v_cvt_pk_bf16_f32 v90, v96, v97
	v_cvt_pk_bf16_f32 v91, v98, v99
	global_store_dwordx4 v[100:101], v[88:91], off
	v_mov_b32_e32 v92, v151
	v_ashrrev_i32_e32 v103, 31, v102
	v_lshl_add_u64 v[88:89], v[102:103], 4, s[4:5]
	v_mov_b32_e32 v94, v152
	v_ashrrev_i32_e32 v93, 31, v92
	v_lshl_add_u64 v[92:93], v[92:93], 4, s[10:11]
	s_waitcnt vmcnt(23)
; __device__ __forceinline__ float bf_lo(unsigned u) { return __uint_as_float(u << 16); }
; __device__ __forceinline__ float bf_hi(unsigned u) { return __uint_as_float(u & 0xffff0000u); }
; __device__ __forceinline__ int launder_i(int x) { asm volatile("" : "+v"(x)); return x; }
; __device__ void phaseM1(const Params& p, char* lds) {
;     ...
;             if (br == 0) {
; #pragma unroll
;                 for (int mi = 0; mi < 8; mi++)
; #pragma unroll
;                     for (int nh = 0; nh < 2; nh++) {
;                         const u32x4 sg = SG[(size_t)launder_i(pbase + (mi * 2 + nh) * 512)];
;                         const f32x4 a0 = acc[mi][2 * nh], a1 = acc[mi][2 * nh + 1];
;                         PA[(size_t)launder_i(pbase + (mi * 2 + nh) * 512)] = (u32x4){pack2(bf_lo(sg.x) * a0[0], bf_hi(sg.x) * a0[1]), pack2(bf_lo(sg.y) * a0[2], bf_hi(sg.y) * a0[3]),
;                                                                           pack2(bf_lo(sg.z) * a1[0], bf_hi(sg.z) * a1[1]), pack2(bf_lo(sg.w) * a1[2], bf_hi(sg.w) * a1[3])};
;                     }
	v_mov_b32_e32 v88, v204
	v_mov_b32_e32 v89, v205
	v_mov_b32_e32 v90, v206
	v_mov_b32_e32 v91, v207
	v_lshlrev_b32_e32 v96, 16, v88
	v_and_b32_e32 v97, 0xffff0000, v88
	v_lshlrev_b32_e32 v88, 16, v89
	v_and_b32_e32 v89, 0xffff0000, v89
	v_lshlrev_b32_e32 v98, 16, v90
	v_and_b32_e32 v99, 0xffff0000, v90
	v_lshlrev_b32_e32 v90, 16, v91
	v_and_b32_e32 v91, 0xffff0000, v91
	v_pk_mul_f32 v[84:85], v[84:85], v[96:97]
	v_pk_mul_f32 v[86:87], v[86:87], v[88:89]
	v_pk_mul_f32 v[88:89], v[80:81], v[98:99]
	v_pk_mul_f32 v[90:91], v[82:83], v[90:91]
	v_cvt_pk_bf16_f32 v80, v84, v85
	v_cvt_pk_bf16_f32 v81, v86, v87
	v_cvt_pk_bf16_f32 v82, v88, v89
	v_cvt_pk_bf16_f32 v83, v90, v91
	global_store_dwordx4 v[92:93], v[80:83], off
	v_mov_b32_e32 v84, v152
	v_ashrrev_i32_e32 v95, 31, v94
	v_lshl_add_u64 v[80:81], v[94:95], 4, s[4:5]
	v_mov_b32_e32 v86, v153
	v_ashrrev_i32_e32 v85, 31, v84
	v_lshl_add_u64 v[84:85], v[84:85], 4, s[10:11]
	s_waitcnt vmcnt(23)
	v_mov_b32_e32 v80, v208
	v_mov_b32_e32 v81, v209
	v_mov_b32_e32 v82, v210
	v_mov_b32_e32 v83, v211
	v_lshlrev_b32_e32 v88, 16, v80
	v_and_b32_e32 v89, 0xffff0000, v80
	v_lshlrev_b32_e32 v80, 16, v81
	v_and_b32_e32 v81, 0xffff0000, v81
	v_lshlrev_b32_e32 v90, 16, v82
	v_and_b32_e32 v91, 0xffff0000, v82
	v_lshlrev_b32_e32 v82, 16, v83
	v_and_b32_e32 v83, 0xffff0000, v83
	v_pk_mul_f32 v[76:77], v[76:77], v[88:89]
	v_pk_mul_f32 v[78:79], v[78:79], v[80:81]
	v_pk_mul_f32 v[80:81], v[72:73], v[90:91]
	v_pk_mul_f32 v[82:83], v[74:75], v[82:83]
	v_cvt_pk_bf16_f32 v72, v76, v77
	v_cvt_pk_bf16_f32 v73, v78, v79
	v_cvt_pk_bf16_f32 v74, v80, v81
	v_cvt_pk_bf16_f32 v75, v82, v83
	global_store_dwordx4 v[84:85], v[72:75], off
	v_mov_b32_e32 v76, v153
	v_ashrrev_i32_e32 v87, 31, v86
	v_lshl_add_u64 v[72:73], v[86:87], 4, s[4:5]
	v_mov_b32_e32 v78, v154
	v_ashrrev_i32_e32 v77, 31, v76
	v_lshl_add_u64 v[76:77], v[76:77], 4, s[10:11]
	s_waitcnt vmcnt(23)
	v_mov_b32_e32 v72, v212
	v_mov_b32_e32 v73, v213
	v_mov_b32_e32 v74, v214
	v_mov_b32_e32 v75, v215
	v_lshlrev_b32_e32 v80, 16, v72
	v_and_b32_e32 v81, 0xffff0000, v72
	v_lshlrev_b32_e32 v72, 16, v73
	v_and_b32_e32 v73, 0xffff0000, v73
	v_lshlrev_b32_e32 v82, 16, v74
	v_and_b32_e32 v83, 0xffff0000, v74
	v_lshlrev_b32_e32 v74, 16, v75
	v_and_b32_e32 v75, 0xffff0000, v75
	v_pk_mul_f32 v[64:65], v[64:65], v[80:81]
	v_pk_mul_f32 v[66:67], v[66:67], v[72:73]
	v_pk_mul_f32 v[68:69], v[68:69], v[82:83]
	v_pk_mul_f32 v[70:71], v[70:71], v[74:75]
	v_cvt_pk_bf16_f32 v64, v64, v65
	v_cvt_pk_bf16_f32 v65, v66, v67
	v_cvt_pk_bf16_f32 v66, v68, v69
	v_cvt_pk_bf16_f32 v67, v70, v71
	global_store_dwordx4 v[76:77], v[64:67], off
	v_mov_b32_e32 v68, v154
	v_ashrrev_i32_e32 v79, 31, v78
	v_lshl_add_u64 v[64:65], v[78:79], 4, s[4:5]
	v_mov_b32_e32 v70, v155
	v_ashrrev_i32_e32 v69, 31, v68
	v_lshl_add_u64 v[68:69], v[68:69], 4, s[10:11]
	s_waitcnt vmcnt(23)
	v_mov_b32_e32 v64, v216
	v_mov_b32_e32 v65, v217
	v_mov_b32_e32 v66, v218
	v_mov_b32_e32 v67, v219
	v_lshlrev_b32_e32 v72, 16, v64
	v_and_b32_e32 v73, 0xffff0000, v64
	v_lshlrev_b32_e32 v64, 16, v65
	v_and_b32_e32 v65, 0xffff0000, v65
	v_lshlrev_b32_e32 v74, 16, v66
	v_and_b32_e32 v75, 0xffff0000, v66
	v_lshlrev_b32_e32 v66, 16, v67
	v_and_b32_e32 v67, 0xffff0000, v67
	v_pk_mul_f32 v[60:61], v[60:61], v[72:73]
	v_pk_mul_f32 v[62:63], v[62:63], v[64:65]
	v_pk_mul_f32 v[64:65], v[56:57], v[74:75]
	v_pk_mul_f32 v[66:67], v[58:59], v[66:67]
	v_cvt_pk_bf16_f32 v56, v60, v61
	v_cvt_pk_bf16_f32 v57, v62, v63
	v_cvt_pk_bf16_f32 v58, v64, v65
	v_cvt_pk_bf16_f32 v59, v66, v67
	global_store_dwordx4 v[68:69], v[56:59], off
	v_mov_b32_e32 v60, v155
	v_ashrrev_i32_e32 v71, 31, v70
	v_lshl_add_u64 v[56:57], v[70:71], 4, s[4:5]
	v_mov_b32_e32 v62, v156
	v_ashrrev_i32_e32 v61, 31, v60
	v_lshl_add_u64 v[60:61], v[60:61], 4, s[10:11]
	s_waitcnt vmcnt(23)
	v_mov_b32_e32 v56, v224
	v_mov_b32_e32 v57, v225
	v_mov_b32_e32 v58, v226
	v_mov_b32_e32 v59, v227
	v_lshlrev_b32_e32 v64, 16, v56
	v_and_b32_e32 v65, 0xffff0000, v56
	v_lshlrev_b32_e32 v56, 16, v57
	v_and_b32_e32 v57, 0xffff0000, v57
	v_lshlrev_b32_e32 v66, 16, v58
	v_and_b32_e32 v67, 0xffff0000, v58
	v_lshlrev_b32_e32 v58, 16, v59
	v_and_b32_e32 v59, 0xffff0000, v59
	v_pk_mul_f32 v[52:53], v[52:53], v[64:65]
	v_pk_mul_f32 v[54:55], v[54:55], v[56:57]
	v_pk_mul_f32 v[56:57], v[48:49], v[66:67]
	v_pk_mul_f32 v[58:59], v[50:51], v[58:59]
	v_cvt_pk_bf16_f32 v48, v52, v53
	v_cvt_pk_bf16_f32 v49, v54, v55
	v_cvt_pk_bf16_f32 v50, v56, v57
	v_cvt_pk_bf16_f32 v51, v58, v59
	global_store_dwordx4 v[60:61], v[48:51], off
	v_mov_b32_e32 v52, v156
	v_ashrrev_i32_e32 v63, 31, v62
	v_lshl_add_u64 v[48:49], v[62:63], 4, s[4:5]
	v_mov_b32_e32 v54, v157
	v_ashrrev_i32_e32 v53, 31, v52
	v_lshl_add_u64 v[52:53], v[52:53], 4, s[10:11]
	s_waitcnt vmcnt(23)
; __device__ __forceinline__ float bf_lo(unsigned u) { return __uint_as_float(u << 16); }
; __device__ __forceinline__ float bf_hi(unsigned u) { return __uint_as_float(u & 0xffff0000u); }
; __device__ __forceinline__ int launder_i(int x) { asm volatile("" : "+v"(x)); return x; }
; __device__ void phaseM1(const Params& p, char* lds) {
;     ...
;             if (br == 0) {
; #pragma unroll
;                 for (int mi = 0; mi < 8; mi++)
; #pragma unroll
;                     for (int nh = 0; nh < 2; nh++) {
;                         const u32x4 sg = SG[(size_t)launder_i(pbase + (mi * 2 + nh) * 512)];
;                         const f32x4 a0 = acc[mi][2 * nh], a1 = acc[mi][2 * nh + 1];
;                         PA[(size_t)launder_i(pbase + (mi * 2 + nh) * 512)] = (u32x4){pack2(bf_lo(sg.x) * a0[0], bf_hi(sg.x) * a0[1]), pack2(bf_lo(sg.y) * a0[2], bf_hi(sg.y) * a0[3]),
;                                                                           pack2(bf_lo(sg.z) * a1[0], bf_hi(sg.z) * a1[1]), pack2(bf_lo(sg.w) * a1[2], bf_hi(sg.w) * a1[3])};
;                     }
	v_mov_b32_e32 v48, v228
	v_mov_b32_e32 v49, v229
	v_mov_b32_e32 v50, v230
	v_mov_b32_e32 v51, v231
	v_lshlrev_b32_e32 v56, 16, v48
	v_and_b32_e32 v57, 0xffff0000, v48
	v_lshlrev_b32_e32 v48, 16, v49
	v_and_b32_e32 v49, 0xffff0000, v49
	v_lshlrev_b32_e32 v58, 16, v50
	v_and_b32_e32 v59, 0xffff0000, v50
	v_lshlrev_b32_e32 v50, 16, v51
	v_and_b32_e32 v51, 0xffff0000, v51
	v_pk_mul_f32 v[44:45], v[44:45], v[56:57]
	v_pk_mul_f32 v[46:47], v[46:47], v[48:49]
	v_pk_mul_f32 v[48:49], v[40:41], v[58:59]
	v_pk_mul_f32 v[50:51], v[42:43], v[50:51]
	v_cvt_pk_bf16_f32 v40, v44, v45
	v_cvt_pk_bf16_f32 v41, v46, v47
	v_cvt_pk_bf16_f32 v42, v48, v49
	v_cvt_pk_bf16_f32 v43, v50, v51
	global_store_dwordx4 v[52:53], v[40:43], off
	v_mov_b32_e32 v44, v157
	v_ashrrev_i32_e32 v55, 31, v54
	v_lshl_add_u64 v[40:41], v[54:55], 4, s[4:5]
	v_mov_b32_e32 v46, v160
	v_ashrrev_i32_e32 v45, 31, v44
	v_lshl_add_u64 v[44:45], v[44:45], 4, s[10:11]
	s_waitcnt vmcnt(23)
	v_mov_b32_e32 v40, v232
	v_mov_b32_e32 v41, v233
	v_mov_b32_e32 v42, v234
	v_mov_b32_e32 v43, v235
	v_lshlrev_b32_e32 v48, 16, v40
	v_and_b32_e32 v49, 0xffff0000, v40
	v_lshlrev_b32_e32 v40, 16, v41
	v_and_b32_e32 v41, 0xffff0000, v41
	v_lshlrev_b32_e32 v50, 16, v42
	v_and_b32_e32 v51, 0xffff0000, v42
	v_lshlrev_b32_e32 v42, 16, v43
	v_and_b32_e32 v43, 0xffff0000, v43
	v_pk_mul_f32 v[36:37], v[36:37], v[48:49]
	v_pk_mul_f32 v[38:39], v[38:39], v[40:41]
	v_pk_mul_f32 v[40:41], v[32:33], v[50:51]
	v_pk_mul_f32 v[42:43], v[34:35], v[42:43]
	v_cvt_pk_bf16_f32 v32, v36, v37
	v_cvt_pk_bf16_f32 v33, v38, v39
	v_cvt_pk_bf16_f32 v34, v40, v41
	v_cvt_pk_bf16_f32 v35, v42, v43
	global_store_dwordx4 v[44:45], v[32:35], off
	v_mov_b32_e32 v36, v160
	v_ashrrev_i32_e32 v47, 31, v46
	v_lshl_add_u64 v[32:33], v[46:47], 4, s[4:5]
	v_mov_b32_e32 v38, v161
	v_ashrrev_i32_e32 v37, 31, v36
	v_lshl_add_u64 v[36:37], v[36:37], 4, s[10:11]
	s_waitcnt vmcnt(23)
	v_mov_b32_e32 v32, v236
	v_mov_b32_e32 v33, v237
	v_mov_b32_e32 v34, v238
	v_mov_b32_e32 v35, v239
	v_lshlrev_b32_e32 v40, 16, v32
	v_and_b32_e32 v41, 0xffff0000, v32
	v_lshlrev_b32_e32 v32, 16, v33
	v_and_b32_e32 v33, 0xffff0000, v33
	v_lshlrev_b32_e32 v42, 16, v34
	v_and_b32_e32 v43, 0xffff0000, v34
	v_lshlrev_b32_e32 v34, 16, v35
	v_and_b32_e32 v35, 0xffff0000, v35
	v_pk_mul_f32 v[28:29], v[28:29], v[40:41]
	v_pk_mul_f32 v[30:31], v[30:31], v[32:33]
	v_pk_mul_f32 v[32:33], v[24:25], v[42:43]
	v_pk_mul_f32 v[34:35], v[26:27], v[34:35]
	v_cvt_pk_bf16_f32 v24, v28, v29
	v_cvt_pk_bf16_f32 v25, v30, v31
	v_cvt_pk_bf16_f32 v26, v32, v33
	v_cvt_pk_bf16_f32 v27, v34, v35
	global_store_dwordx4 v[36:37], v[24:27], off
	v_mov_b32_e32 v28, v161
	v_ashrrev_i32_e32 v39, 31, v38
	v_lshl_add_u64 v[24:25], v[38:39], 4, s[4:5]
	v_mov_b32_e32 v30, v162
	v_ashrrev_i32_e32 v29, 31, v28
	v_lshl_add_u64 v[28:29], v[28:29], 4, s[10:11]
	s_waitcnt vmcnt(23)
	v_mov_b32_e32 v24, v240
	v_mov_b32_e32 v25, v241
	v_mov_b32_e32 v26, v242
	v_mov_b32_e32 v27, v243
	v_lshlrev_b32_e32 v32, 16, v24
	v_and_b32_e32 v33, 0xffff0000, v24
	v_lshlrev_b32_e32 v24, 16, v25
	v_and_b32_e32 v25, 0xffff0000, v25
	v_lshlrev_b32_e32 v34, 16, v26
	v_and_b32_e32 v35, 0xffff0000, v26
	v_lshlrev_b32_e32 v26, 16, v27
	v_and_b32_e32 v27, 0xffff0000, v27
	v_pk_mul_f32 v[20:21], v[20:21], v[32:33]
	v_pk_mul_f32 v[22:23], v[22:23], v[24:25]
	v_pk_mul_f32 v[24:25], v[16:17], v[34:35]
	v_pk_mul_f32 v[26:27], v[18:19], v[26:27]
	v_cvt_pk_bf16_f32 v16, v20, v21
	v_cvt_pk_bf16_f32 v17, v22, v23
	v_cvt_pk_bf16_f32 v18, v24, v25
	v_cvt_pk_bf16_f32 v19, v26, v27
	global_store_dwordx4 v[28:29], v[16:19], off
	v_mov_b32_e32 v20, v162
	v_ashrrev_i32_e32 v31, 31, v30
	v_lshl_add_u64 v[16:17], v[30:31], 4, s[4:5]
	v_mov_b32_e32 v22, v163
	v_ashrrev_i32_e32 v21, 31, v20
	v_lshl_add_u64 v[20:21], v[20:21], 4, s[10:11]
	s_waitcnt vmcnt(23)
	v_mov_b32_e32 v16, v244
	v_mov_b32_e32 v17, v245
	v_mov_b32_e32 v18, v246
	v_mov_b32_e32 v19, v247
	v_lshlrev_b32_e32 v24, 16, v16
	v_and_b32_e32 v25, 0xffff0000, v16
	v_lshlrev_b32_e32 v16, 16, v17
	v_and_b32_e32 v17, 0xffff0000, v17
	v_lshlrev_b32_e32 v26, 16, v18
	v_and_b32_e32 v27, 0xffff0000, v18
	v_lshlrev_b32_e32 v18, 16, v19
	v_and_b32_e32 v19, 0xffff0000, v19
	v_pk_mul_f32 v[12:13], v[12:13], v[24:25]
	v_pk_mul_f32 v[14:15], v[14:15], v[16:17]
	v_pk_mul_f32 v[16:17], v[8:9], v[26:27]
	v_pk_mul_f32 v[18:19], v[10:11], v[18:19]
	v_cvt_pk_bf16_f32 v8, v12, v13
	v_cvt_pk_bf16_f32 v9, v14, v15
	v_cvt_pk_bf16_f32 v10, v16, v17
	v_cvt_pk_bf16_f32 v11, v18, v19
	global_store_dwordx4 v[20:21], v[8:11], off
	v_mov_b32_e32 v12, v163
	v_ashrrev_i32_e32 v23, 31, v22
	v_lshl_add_u64 v[8:9], v[22:23], 4, s[4:5]
	s_waitcnt vmcnt(23)
	v_mov_b32_e32 v8, v248
	v_mov_b32_e32 v9, v249
	v_mov_b32_e32 v10, v250
	v_mov_b32_e32 v11, v251
	v_lshlrev_b32_e32 v14, 16, v8
	v_and_b32_e32 v15, 0xffff0000, v8
	v_lshlrev_b32_e32 v8, 16, v9
	v_and_b32_e32 v9, 0xffff0000, v9
	v_lshlrev_b32_e32 v16, 16, v10
	v_and_b32_e32 v17, 0xffff0000, v10
	v_lshlrev_b32_e32 v10, 16, v11
	v_and_b32_e32 v11, 0xffff0000, v11
	v_ashrrev_i32_e32 v13, 31, v12
	v_pk_mul_f32 v[4:5], v[4:5], v[14:15]
	v_pk_mul_f32 v[6:7], v[6:7], v[8:9]
	v_pk_mul_f32 v[8:9], v[0:1], v[16:17]
	v_pk_mul_f32 v[10:11], v[2:3], v[10:11]
	v_lshl_add_u64 v[12:13], v[12:13], 4, s[10:11]
	v_cvt_pk_bf16_f32 v0, v4, v5
	v_cvt_pk_bf16_f32 v1, v6, v7
	v_cvt_pk_bf16_f32 v2, v8, v9
	v_cvt_pk_bf16_f32 v3, v10, v11
	global_store_dwordx4 v[12:13], v[0:3], off
	s_branch .LBB0_712
